# chunk QK section: K-block loads of causal block n+1 issued right after block n's MFMAs (spare VGPRs), on top of the previous best
# speedup vs baseline: 1.0038x; 1.0026x over previous
.LBB0_1252:
	s_or_b64 exec, exec, s[56:57]
	s_lshl_b32 s14, s65, 1
	v_lshl_add_u64 v[2:3], v[66:67], 0, s[14:15]
	v_or_b32_e32 v0, s38, v60
	v_mad_u64_u32 v[56:57], s[56:57], v0, s63, v[2:3]
	s_mul_i32 s14, s39, 0x600
	v_add_u32_e32 v91, v73, v62
	v_add_u32_e32 v57, s14, v57
	s_waitcnt lgkmcnt(0)
	s_barrier
	ds_read_b128 v[32:35], v71
	ds_read_b128 v[28:31], v71 offset:64
	ds_read_b128 v[24:27], v71 offset:128
	ds_read_b128 v[20:23], v71 offset:192
	ds_read_b128 v[16:19], v71 offset:256
	ds_read_b128 v[12:15], v71 offset:320
	ds_read_b128 v[8:11], v91 offset:51712
	flat_load_dwordx4 v[36:39], v[56:57]
	flat_load_dwordx4 v[40:43], v[56:57] offset:64
	flat_load_dwordx4 v[44:47], v[56:57] offset:128
	flat_load_dwordx4 v[48:51], v[56:57] offset:192
	flat_load_dwordx4 v[52:55], v[56:57] offset:256
	s_nop 0
	flat_load_dwordx4 v[56:59], v[56:57] offset:320
	ds_read_b32 v0, v75 offset:51200
	s_waitcnt vmcnt(0) lgkmcnt(0)
	v_mfma_f32_16x16x32_bf16 v[36:39], v[32:35], v[36:39], 0
	v_mfma_f32_16x16x32_bf16 v[36:39], v[28:31], v[40:43], v[36:39]
	v_sub_f32_e32 v40, v0, v8
	v_mul_f32_e32 v40, 0x3fb8aa3b, v40
	v_exp_f32_e32 v40, v40
	v_mfma_f32_16x16x32_bf16 v[36:39], v[24:27], v[44:47], v[36:39]
	v_mov_b32_e32 v41, 0
	v_mfma_f32_16x16x32_bf16 v[36:39], v[20:23], v[48:51], v[36:39]
	v_mfma_f32_16x16x32_bf16 v[36:39], v[16:19], v[52:55], v[36:39]
	v_mfma_f32_16x16x32_bf16 v[36:39], v[12:15], v[56:59], v[36:39]
	s_mov_b64 vcc, s[30:31]
	s_and_saveexec_b64 s[56:57], vcc
	v_or_b32_e32 v46, s38, v68
	v_mad_u64_u32 v[46:47], s[58:59], v46, s63, v[2:3]
	v_add_u32_e32 v47, s14, v47
	global_load_dwordx4 v[164:167], v[46:47], off
	global_load_dwordx4 v[168:171], v[46:47], off offset:64
	global_load_dwordx4 v[148:151], v[46:47], off offset:128
	global_load_dwordx4 v[152:155], v[46:47], off offset:192
	global_load_dwordx4 v[156:159], v[46:47], off offset:256
	global_load_dwordx4 v[160:163], v[46:47], off offset:320
	s_or_b64 exec, exec, s[56:57]
	s_nop 7
	v_mul_f32_e32 v36, v36, v40
	v_cndmask_b32_e64 v36, v36, 0, s[22:23]
	v_bfe_u32 v40, v36, 16, 1
	v_add3_u32 v36, v36, v40, s64
	ds_write_b16_d16_hi v101, v36 offset:55808
	v_sub_f32_e32 v36, v0, v9
	v_mul_f32_e32 v36, 0x3fb8aa3b, v36
	v_exp_f32_e32 v36, v36
	v_mov_b32_e32 v40, 0
	v_mul_f32_e32 v36, v37, v36
	v_cndmask_b32_e64 v36, v36, 0, s[24:25]
	v_bfe_u32 v37, v36, 16, 1
	v_add3_u32 v36, v36, v37, s64
	ds_write_b16_d16_hi v101, v36 offset:56080
	v_sub_f32_e32 v36, v0, v10
	v_mul_f32_e32 v36, 0x3fb8aa3b, v36
	v_exp_f32_e32 v36, v36
	v_sub_f32_e32 v0, v0, v11
	v_mul_f32_e32 v0, 0x3fb8aa3b, v0
	v_exp_f32_e32 v0, v0
	v_mul_f32_e32 v36, v38, v36
	v_cndmask_b32_e64 v36, v36, 0, s[26:27]
	v_bfe_u32 v37, v36, 16, 1
	v_mul_f32_e32 v0, v39, v0
	v_add3_u32 v36, v36, v37, s64
	v_cndmask_b32_e64 v0, v0, 0, s[28:29]
	ds_write_b16_d16_hi v101, v36 offset:56352
	v_bfe_u32 v36, v0, 16, 1
	v_add3_u32 v0, v0, v36, s64
	v_mov_b32_e32 v36, 0
	v_mov_b32_e32 v38, 0
	v_mov_b32_e32 v39, 0
	ds_write_b16_d16_hi v101, v0 offset:56624
	s_and_saveexec_b64 s[56:57], s[30:31]
	s_cbranch_execz .LBB0_1254
	s_waitcnt vmcnt(0) lgkmcnt(0)
	v_mfma_f32_16x16x32_bf16 v[38:41], v[32:35], v[164:167], 0
	v_mfma_f32_16x16x32_bf16 v[38:41], v[28:31], v[168:171], v[38:41]
	v_mfma_f32_16x16x32_bf16 v[38:41], v[24:27], v[148:151], v[38:41]
	v_mfma_f32_16x16x32_bf16 v[38:41], v[20:23], v[152:155], v[38:41]
	v_mfma_f32_16x16x32_bf16 v[38:41], v[16:19], v[156:159], v[38:41]
	v_mfma_f32_16x16x32_bf16 v[38:41], v[12:15], v[160:163], v[38:41]
.LBB0_1254:
	s_or_b64 exec, exec, s[56:57]
	v_readlane_b32 vcc_lo, v252, 20
	v_readlane_b32 vcc_hi, v252, 21
	s_nop 3
	s_and_saveexec_b64 s[56:57], vcc
	v_or_b32_e32 v46, s38, v70
	v_mad_u64_u32 v[46:47], s[58:59], v46, s63, v[2:3]
	v_add_u32_e32 v47, s14, v47
	global_load_dwordx4 v[164:167], v[46:47], off
	global_load_dwordx4 v[168:171], v[46:47], off offset:64
	global_load_dwordx4 v[148:151], v[46:47], off offset:128
	global_load_dwordx4 v[152:155], v[46:47], off offset:192
	global_load_dwordx4 v[156:159], v[46:47], off offset:256
	global_load_dwordx4 v[160:163], v[46:47], off offset:320
	s_or_b64 exec, exec, s[56:57]
	ds_read_b32 v0, v75 offset:51264
	v_readlane_b32 s40, v252, 30
	v_readlane_b32 s41, v252, 31
	s_waitcnt lgkmcnt(0)
	v_sub_f32_e32 v37, v0, v8
	v_mul_f32_e32 v37, 0x3fb8aa3b, v37
	v_exp_f32_e32 v37, v37
	s_nop 0
	v_mul_f32_e32 v37, v38, v37
	v_cndmask_b32_e64 v37, v37, 0, s[40:41]
	v_bfe_u32 v38, v37, 16, 1
	v_add3_u32 v37, v37, v38, s64
	ds_write_b16_d16_hi v104, v37 offset:55840
	v_sub_f32_e32 v37, v0, v9
	v_mul_f32_e32 v37, 0x3fb8aa3b, v37
	v_exp_f32_e32 v37, v37
	v_readlane_b32 s40, v252, 32
	v_readlane_b32 s41, v252, 33
	v_mul_f32_e32 v37, v39, v37
	s_nop 0
	v_cndmask_b32_e64 v37, v37, 0, s[40:41]
	v_bfe_u32 v38, v37, 16, 1
	v_add3_u32 v37, v37, v38, s64
	ds_write_b16_d16_hi v104, v37 offset:56112
	v_sub_f32_e32 v37, v0, v10
	v_mul_f32_e32 v37, 0x3fb8aa3b, v37
	v_exp_f32_e32 v37, v37
	v_sub_f32_e32 v0, v0, v11
	v_mul_f32_e32 v0, 0x3fb8aa3b, v0
	v_exp_f32_e32 v0, v0
	v_readlane_b32 s40, v252, 34
	v_mul_f32_e32 v37, v40, v37
	v_readlane_b32 s41, v252, 35
	v_mul_f32_e32 v0, v41, v0
	v_mov_b32_e32 v39, 0
	v_cndmask_b32_e64 v37, v37, 0, s[40:41]
	v_readlane_b32 s40, v252, 36
	v_bfe_u32 v38, v37, 16, 1
	v_readlane_b32 s41, v252, 37
	v_add3_u32 v37, v37, v38, s64
	ds_write_b16_d16_hi v104, v37 offset:56384
	v_cndmask_b32_e64 v0, v0, 0, s[40:41]
	v_bfe_u32 v37, v0, 16, 1
	v_readlane_b32 s40, v252, 20
	v_add3_u32 v0, v0, v37, s64
	v_mov_b32_e32 v38, 0
	v_mov_b32_e32 v40, 0
	v_mov_b32_e32 v41, 0
	v_readlane_b32 s41, v252, 21
	ds_write_b16_d16_hi v104, v0 offset:56656
	s_and_saveexec_b64 s[56:57], s[40:41]
	s_cbranch_execz .LBB0_1256
	s_waitcnt vmcnt(0) lgkmcnt(0)
	v_mfma_f32_16x16x32_bf16 v[38:41], v[32:35], v[164:167], 0
	v_mfma_f32_16x16x32_bf16 v[38:41], v[28:31], v[168:171], v[38:41]
	v_mfma_f32_16x16x32_bf16 v[38:41], v[24:27], v[148:151], v[38:41]
	v_mfma_f32_16x16x32_bf16 v[38:41], v[20:23], v[152:155], v[38:41]
	v_mfma_f32_16x16x32_bf16 v[38:41], v[16:19], v[156:159], v[38:41]
	v_mfma_f32_16x16x32_bf16 v[38:41], v[12:15], v[160:163], v[38:41]
.LBB0_1256:
	s_or_b64 exec, exec, s[56:57]
	v_readlane_b32 vcc_lo, v252, 22
	v_readlane_b32 vcc_hi, v252, 23
	s_nop 3
	s_and_saveexec_b64 s[56:57], vcc
	v_or_b32_e32 v46, s38, v72
	v_mad_u64_u32 v[46:47], s[58:59], v46, s63, v[2:3]
	v_add_u32_e32 v47, s14, v47
	global_load_dwordx4 v[164:167], v[46:47], off
	global_load_dwordx4 v[168:171], v[46:47], off offset:64
	global_load_dwordx4 v[148:151], v[46:47], off offset:128
	global_load_dwordx4 v[152:155], v[46:47], off offset:192
	global_load_dwordx4 v[156:159], v[46:47], off offset:256
	global_load_dwordx4 v[160:163], v[46:47], off offset:320
	s_or_b64 exec, exec, s[56:57]
	ds_read_b32 v0, v75 offset:51328
	v_readlane_b32 s40, v252, 38
	v_readlane_b32 s41, v252, 39
	s_waitcnt lgkmcnt(0)
	v_sub_f32_e32 v37, v0, v8
	v_mul_f32_e32 v37, 0x3fb8aa3b, v37
	v_exp_f32_e32 v37, v37
	s_nop 0
	v_mul_f32_e32 v37, v38, v37
	v_cndmask_b32_e64 v37, v37, 0, s[40:41]
	v_bfe_u32 v38, v37, 16, 1
	v_add3_u32 v37, v37, v38, s64
	ds_write_b16_d16_hi v104, v37 offset:55872
	v_sub_f32_e32 v37, v0, v9
	v_mul_f32_e32 v37, 0x3fb8aa3b, v37
	v_exp_f32_e32 v37, v37
	v_readlane_b32 s40, v252, 40
	v_readlane_b32 s41, v252, 41
	v_mul_f32_e32 v37, v39, v37
	s_nop 0
	v_cndmask_b32_e64 v37, v37, 0, s[40:41]
	v_bfe_u32 v38, v37, 16, 1
	v_add3_u32 v37, v37, v38, s64
	ds_write_b16_d16_hi v104, v37 offset:56144
	v_sub_f32_e32 v37, v0, v10
	v_mul_f32_e32 v37, 0x3fb8aa3b, v37
	v_exp_f32_e32 v37, v37
	v_sub_f32_e32 v0, v0, v11
	v_mul_f32_e32 v0, 0x3fb8aa3b, v0
	v_exp_f32_e32 v0, v0
	v_mul_f32_e32 v37, v40, v37
	v_cndmask_b32_e64 v37, v37, 0, s[8:9]
	v_bfe_u32 v38, v37, 16, 1
	v_mul_f32_e32 v0, v41, v0
	v_add3_u32 v37, v37, v38, s64
	v_cndmask_b32_e64 v0, v0, 0, s[10:11]
	ds_write_b16_d16_hi v104, v37 offset:56416
	v_bfe_u32 v37, v0, 16, 1
	v_readlane_b32 s40, v252, 22
	v_add3_u32 v0, v0, v37, s64
	v_mov_b32_e32 v37, 0
	v_mov_b32_e32 v38, 0
	v_mov_b32_e32 v39, 0
	v_readlane_b32 s41, v252, 23
	ds_write_b16_d16_hi v104, v0 offset:56688
	s_and_saveexec_b64 s[56:57], s[40:41]
	s_cbranch_execz .LBB0_1258
	s_waitcnt vmcnt(0) lgkmcnt(0)
	v_mfma_f32_16x16x32_bf16 v[36:39], v[32:35], v[164:167], 0
	v_mfma_f32_16x16x32_bf16 v[36:39], v[28:31], v[168:171], v[36:39]
	v_mfma_f32_16x16x32_bf16 v[36:39], v[24:27], v[148:151], v[36:39]
	v_mfma_f32_16x16x32_bf16 v[36:39], v[20:23], v[152:155], v[36:39]
	v_mfma_f32_16x16x32_bf16 v[36:39], v[16:19], v[156:159], v[36:39]
	v_mfma_f32_16x16x32_bf16 v[36:39], v[12:15], v[160:163], v[36:39]
.LBB0_1258:
	s_or_b64 exec, exec, s[56:57]
	s_mov_b64 vcc, s[34:35]
	s_and_saveexec_b64 s[56:57], vcc
	v_or_b32_e32 v46, s38, v74
	v_mad_u64_u32 v[46:47], s[58:59], v46, s63, v[2:3]
	v_add_u32_e32 v47, s14, v47
	global_load_dwordx4 v[164:167], v[46:47], off
	global_load_dwordx4 v[168:171], v[46:47], off offset:64
	global_load_dwordx4 v[148:151], v[46:47], off offset:128
	global_load_dwordx4 v[152:155], v[46:47], off offset:192
	global_load_dwordx4 v[156:159], v[46:47], off offset:256
	global_load_dwordx4 v[160:163], v[46:47], off offset:320
	s_or_b64 exec, exec, s[56:57]
	ds_read_b32 v0, v75 offset:51392
	v_readlane_b32 s40, v252, 42
	v_readlane_b32 s41, v252, 43
	v_mov_b32_e32 v41, 0
	s_waitcnt lgkmcnt(0)
	v_sub_f32_e32 v40, v0, v8
	v_mul_f32_e32 v40, 0x3fb8aa3b, v40
	v_exp_f32_e32 v40, v40
	s_nop 0
	v_mul_f32_e32 v36, v36, v40
	v_cndmask_b32_e64 v36, v36, 0, s[40:41]
	v_bfe_u32 v40, v36, 16, 1
	v_add3_u32 v36, v36, v40, s64
	ds_write_b16_d16_hi v104, v36 offset:55904
	v_sub_f32_e32 v36, v0, v9
	v_mul_f32_e32 v36, 0x3fb8aa3b, v36
	v_exp_f32_e32 v36, v36
	v_readlane_b32 s40, v252, 44
	v_readlane_b32 s41, v252, 45
	v_mov_b32_e32 v40, 0
	v_mul_f32_e32 v36, v37, v36
	v_cndmask_b32_e64 v36, v36, 0, s[40:41]
	v_bfe_u32 v37, v36, 16, 1
	v_add3_u32 v36, v36, v37, s64
	ds_write_b16_d16_hi v104, v36 offset:56176
	v_sub_f32_e32 v36, v0, v10
	v_mul_f32_e32 v36, 0x3fb8aa3b, v36
	v_exp_f32_e32 v36, v36
	v_sub_f32_e32 v0, v0, v11
	v_mul_f32_e32 v0, 0x3fb8aa3b, v0
	v_exp_f32_e32 v0, v0
	v_mul_f32_e32 v36, v38, v36
	v_cndmask_b32_e64 v36, v36, 0, s[86:87]
	v_bfe_u32 v37, v36, 16, 1
	v_mul_f32_e32 v0, v39, v0
	v_add3_u32 v36, v36, v37, s64
	v_cndmask_b32_e64 v0, v0, 0, s[88:89]
	ds_write_b16_d16_hi v104, v36 offset:56448
	v_bfe_u32 v36, v0, 16, 1
	v_add3_u32 v0, v0, v36, s64
	v_mov_b32_e32 v36, 0
	v_mov_b32_e32 v38, 0
	v_mov_b32_e32 v39, 0
	ds_write_b16_d16_hi v104, v0 offset:56720
	s_and_saveexec_b64 s[56:57], s[34:35]
	s_cbranch_execz .LBB0_1260
	s_waitcnt vmcnt(0) lgkmcnt(0)
	v_mfma_f32_16x16x32_bf16 v[38:41], v[32:35], v[164:167], 0
	v_mfma_f32_16x16x32_bf16 v[38:41], v[28:31], v[168:171], v[38:41]
	v_mfma_f32_16x16x32_bf16 v[38:41], v[24:27], v[148:151], v[38:41]
	v_mfma_f32_16x16x32_bf16 v[38:41], v[20:23], v[152:155], v[38:41]
	v_mfma_f32_16x16x32_bf16 v[38:41], v[16:19], v[156:159], v[38:41]
	v_mfma_f32_16x16x32_bf16 v[38:41], v[12:15], v[160:163], v[38:41]
.LBB0_1260:
	s_or_b64 exec, exec, s[56:57]
	v_readlane_b32 vcc_lo, v252, 24
	v_readlane_b32 vcc_hi, v252, 25
	s_nop 3
	s_and_saveexec_b64 s[56:57], vcc
	v_or_b32_e32 v46, s38, v76
	v_mad_u64_u32 v[46:47], s[58:59], v46, s63, v[2:3]
	v_add_u32_e32 v47, s14, v47
	global_load_dwordx4 v[164:167], v[46:47], off
	global_load_dwordx4 v[168:171], v[46:47], off offset:64
	global_load_dwordx4 v[148:151], v[46:47], off offset:128
	global_load_dwordx4 v[152:155], v[46:47], off offset:192
	global_load_dwordx4 v[156:159], v[46:47], off offset:256
	global_load_dwordx4 v[160:163], v[46:47], off offset:320
	s_or_b64 exec, exec, s[56:57]
	ds_read_b32 v0, v75 offset:51456
	v_readlane_b32 s40, v252, 24
	v_readlane_b32 s41, v252, 25
	s_waitcnt lgkmcnt(0)
	v_sub_f32_e32 v37, v0, v8
	v_mul_f32_e32 v37, 0x3fb8aa3b, v37
	v_exp_f32_e32 v37, v37
	s_nop 0
	v_mul_f32_e32 v37, v38, v37
	v_cndmask_b32_e64 v37, v37, 0, s[90:91]
	v_bfe_u32 v38, v37, 16, 1
	v_add3_u32 v37, v37, v38, s64
	ds_write_b16_d16_hi v104, v37 offset:55936
	v_sub_f32_e32 v37, v0, v9
	v_mul_f32_e32 v37, 0x3fb8aa3b, v37
	v_exp_f32_e32 v37, v37
	s_nop 0
	v_mul_f32_e32 v37, v39, v37
	v_cndmask_b32_e64 v37, v37, 0, s[92:93]
	v_bfe_u32 v38, v37, 16, 1
	v_add3_u32 v37, v37, v38, s64
	ds_write_b16_d16_hi v104, v37 offset:56208
	v_sub_f32_e32 v37, v0, v10
	v_mul_f32_e32 v37, 0x3fb8aa3b, v37
	v_exp_f32_e32 v37, v37
	v_sub_f32_e32 v0, v0, v11
	v_mul_f32_e32 v0, 0x3fb8aa3b, v0
	v_exp_f32_e32 v0, v0
	v_mul_f32_e32 v37, v40, v37
	v_cndmask_b32_e64 v37, v37, 0, s[94:95]
	v_bfe_u32 v38, v37, 16, 1
	v_mul_f32_e32 v0, v41, v0
	v_add3_u32 v37, v37, v38, s64
	v_cndmask_b32_e64 v0, v0, 0, s[96:97]
	ds_write_b16_d16_hi v104, v37 offset:56480
	v_bfe_u32 v37, v0, 16, 1
	v_add3_u32 v0, v0, v37, s64
	v_mov_b32_e32 v37, 0
	v_mov_b32_e32 v38, 0
	v_mov_b32_e32 v39, 0
	ds_write_b16_d16_hi v104, v0 offset:56752
	s_and_saveexec_b64 s[56:57], s[40:41]
	s_cbranch_execz .LBB0_1262
	s_waitcnt vmcnt(0) lgkmcnt(0)
	v_mfma_f32_16x16x32_bf16 v[36:39], v[32:35], v[164:167], 0
	v_mfma_f32_16x16x32_bf16 v[36:39], v[28:31], v[168:171], v[36:39]
	v_mfma_f32_16x16x32_bf16 v[36:39], v[24:27], v[148:151], v[36:39]
	v_mfma_f32_16x16x32_bf16 v[36:39], v[20:23], v[152:155], v[36:39]
	v_mfma_f32_16x16x32_bf16 v[36:39], v[16:19], v[156:159], v[36:39]
	v_mfma_f32_16x16x32_bf16 v[36:39], v[12:15], v[160:163], v[36:39]
.LBB0_1262:
	s_or_b64 exec, exec, s[56:57]
	v_readlane_b32 vcc_lo, v252, 26
	v_readlane_b32 vcc_hi, v252, 27
	s_nop 3
	s_and_saveexec_b64 s[56:57], vcc
	v_or_b32_e32 v46, s38, v78
	v_mad_u64_u32 v[46:47], s[58:59], v46, s63, v[2:3]
	v_add_u32_e32 v47, s14, v47
	global_load_dwordx4 v[164:167], v[46:47], off
	global_load_dwordx4 v[168:171], v[46:47], off offset:64
	global_load_dwordx4 v[148:151], v[46:47], off offset:128
	global_load_dwordx4 v[152:155], v[46:47], off offset:192
	global_load_dwordx4 v[156:159], v[46:47], off offset:256
	global_load_dwordx4 v[160:163], v[46:47], off offset:320
	s_or_b64 exec, exec, s[56:57]
	ds_read_b32 v0, v75 offset:51520
	v_readlane_b32 s40, v252, 26
	v_mov_b32_e32 v41, 0
	v_readlane_b32 s41, v252, 27
	s_waitcnt lgkmcnt(0)
	v_sub_f32_e32 v40, v0, v8
	v_mul_f32_e32 v40, 0x3fb8aa3b, v40
	v_exp_f32_e32 v40, v40
	s_nop 0
	v_mul_f32_e32 v36, v36, v40
	v_cndmask_b32_e64 v36, v36, 0, s[6:7]
	v_bfe_u32 v40, v36, 16, 1
	v_add3_u32 v36, v36, v40, s64
	ds_write_b16_d16_hi v104, v36 offset:55968
	v_sub_f32_e32 v36, v0, v9
	v_mul_f32_e32 v36, 0x3fb8aa3b, v36
	v_exp_f32_e32 v36, v36
	v_mov_b32_e32 v40, 0
	v_mul_f32_e32 v36, v37, v36
	v_cndmask_b32_e64 v36, v36, 0, s[4:5]
	v_bfe_u32 v37, v36, 16, 1
	v_add3_u32 v36, v36, v37, s64
	ds_write_b16_d16_hi v104, v36 offset:56240
	v_sub_f32_e32 v36, v0, v10
	v_mul_f32_e32 v36, 0x3fb8aa3b, v36
	v_exp_f32_e32 v36, v36
	v_sub_f32_e32 v0, v0, v11
	v_mul_f32_e32 v0, 0x3fb8aa3b, v0
	v_exp_f32_e32 v0, v0
	v_mul_f32_e32 v36, v38, v36
	v_cndmask_b32_e64 v36, v36, 0, s[84:85]
	v_bfe_u32 v37, v36, 16, 1
	v_mul_f32_e32 v0, v39, v0
	v_add3_u32 v36, v36, v37, s64
	v_cndmask_b32_e64 v0, v0, 0, s[36:37]
	ds_write_b16_d16_hi v104, v36 offset:56512
	v_bfe_u32 v36, v0, 16, 1
	v_add3_u32 v0, v0, v36, s64
	v_mov_b32_e32 v36, 0
	v_mov_b32_e32 v38, 0
	v_mov_b32_e32 v39, 0
	ds_write_b16_d16_hi v104, v0 offset:56784
	s_and_saveexec_b64 s[56:57], s[40:41]
	s_cbranch_execz .LBB0_1264
	s_waitcnt vmcnt(0) lgkmcnt(0)
	v_mfma_f32_16x16x32_bf16 v[38:41], v[32:35], v[164:167], 0
	v_mfma_f32_16x16x32_bf16 v[38:41], v[28:31], v[168:171], v[38:41]
	v_mfma_f32_16x16x32_bf16 v[38:41], v[24:27], v[148:151], v[38:41]
	v_mfma_f32_16x16x32_bf16 v[38:41], v[20:23], v[152:155], v[38:41]
	v_mfma_f32_16x16x32_bf16 v[38:41], v[16:19], v[156:159], v[38:41]
	v_mfma_f32_16x16x32_bf16 v[38:41], v[12:15], v[160:163], v[38:41]
